# k26 + Hyena gating loops (order 0 and 1, both layers): all seven LDS reads of an iteration issued before the first wait, counted lgkmcnt
# baseline (speedup 1.0000x reference)
.LBB0_1340:
	v_add_u32_e32 v51, 0, v45
	ds_read_b64 v[74:75], v51
	v_add_u32_e32 v51, 0, v47
	ds_read_b64 v[76:77], v51
	v_add_u32_e32 v51, s80, v140
	v_cmp_lt_i32_e32 vcc, 0, v51
	v_add_u32_e32 v59, 0, v49
	v_add_u32_e32 v53, 0, v43
	v_subbrev_co_u32_e64 v55, s[0:1], 0, v51, vcc
	v_lshl_add_u32 v55, v55, 1, 0
	v_add_u32_e32 v57, 0x15400, v55
	v_add_u32_e32 v61, 0x15400, v59
	v_cmp_gt_i32_e64 s[0:1], s3, v51
	v_add_u32_e32 v51, 0x17400, v55
	v_add_u32_e32 v55, 0x17400, v59
	ds_read_b64 v[188:189], v53
	ds_read_b32 v59, v61
	ds_read_u16 v51, v51
	ds_read_u16 v57, v57
	ds_read_b32 v190, v55
	s_addk_i32 s80, 0x100
	v_add_u32_e32 v49, 0x200, v49
	s_waitcnt lgkmcnt(5)
	v_pk_add_f32 v[74:75], v[74:75], v[76:77]
	s_waitcnt lgkmcnt(4)
	v_pk_fma_f32 v[74:75], v[72:73], v[188:189], v[74:75]
	s_waitcnt lgkmcnt(2)
	v_lshlrev_b32_e32 v51, 16, v51
	v_cndmask_b32_e32 v77, 0, v51, vcc
	s_waitcnt lgkmcnt(1)
	v_lshlrev_b32_e32 v57, 16, v57
	v_lshlrev_b32_e32 v78, 16, v59
	v_cndmask_b32_e32 v76, 0, v57, vcc
	v_and_b32_e32 v55, 0xffff0000, v59
	s_waitcnt lgkmcnt(0)
	v_lshlrev_b32_e32 v79, 16, v190
	v_pk_mul_f32 v[78:79], v[30:31], v[78:79]
	v_and_b32_e32 v51, 0xffff0000, v190
	v_pk_fma_f32 v[76:77], v[26:27], v[76:77], v[78:79]
	v_cndmask_b32_e64 v79, 0, v51, s[0:1]
	v_cndmask_b32_e64 v78, 0, v55, s[0:1]
	v_pk_fma_f32 v[76:77], v[32:33], v[78:79], v[76:77]
	v_add_u32_e32 v43, 0x800, v43
	v_pk_add_f32 v[76:77], v[28:29], v[76:77]
	v_add_u32_e32 v47, 0x880, v47
	v_pk_mul_f32 v[74:75], v[74:75], v[76:77]
	v_add_u32_e32 v45, 0x880, v45
	s_cmpk_eq_i32 s80, 0x800
	ds_write_b64 v53, v[74:75]
	s_cbranch_scc0 .LBB0_1340
	v_add_f32_e64 v26, |v34|, |v44|
	v_add_f32_e64 v26, v26, |v42|
	v_add_f32_e64 v26, v26, |v50|
	v_add_f32_e64 v26, v26, |v48|
	v_add_f32_e64 v26, v26, |v56|
	v_add_f32_e64 v26, v26, |v46|
	v_add_f32_e64 v26, v26, |v54|
	v_add_f32_e64 v26, v26, |v52|
	v_add_f32_e64 v26, v26, |v60|
	v_add_f32_e64 v26, v26, |v58|
	v_add_f32_e64 v26, v26, |v64|
	v_add_f32_e64 v26, v26, |v62|
	v_add_f32_e64 v26, v26, |v68|
	v_add_f32_e64 v26, v26, |v66|
	v_add_f32_e64 v26, v26, |v70|
	ds_bpermute_b32 v27, v132, v26
	v_mov_b32_e32 v45, v35
	v_mov_b32_e32 v43, v35
	v_mov_b32_e32 v51, v35
	v_mov_b32_e32 v49, v35
	s_waitcnt lgkmcnt(0)
	v_add_f32_e32 v26, v26, v27
	ds_bpermute_b32 v27, v133, v26
	v_mov_b32_e32 v57, v35
	v_mov_b32_e32 v47, v35
	v_mov_b32_e32 v55, v35
	v_mov_b32_e32 v53, v35
	s_waitcnt lgkmcnt(0)
	v_add_f32_e32 v26, v26, v27
	ds_bpermute_b32 v27, v134, v26
	v_mov_b32_e32 v61, v35
	v_mov_b32_e32 v59, v35
	v_mov_b32_e32 v65, v35
	v_mov_b32_e32 v63, v35
	s_waitcnt lgkmcnt(0)
	v_add_f32_e32 v26, v26, v27
	ds_bpermute_b32 v27, v135, v26
	v_mov_b32_e32 v69, v35
	v_mov_b32_e32 v67, v35
	v_mov_b32_e32 v71, v35
	v_mov_b32_e32 v28, v0
	s_waitcnt lgkmcnt(0)
	v_add_f32_e32 v26, v26, v27
	ds_bpermute_b32 v27, v136, v26
	s_waitcnt lgkmcnt(0)
	s_barrier
	ds_write_b64 v144, v[34:35]
	v_add_f32_e32 v26, v26, v27
	ds_bpermute_b32 v27, v137, v26
	ds_write_b64 v144, v[44:45] offset:2176
	ds_write_b64 v144, v[42:43] offset:4352
	ds_write_b64 v144, v[50:51] offset:6528
	ds_write_b64 v144, v[48:49] offset:8704
	ds_write_b64 v144, v[56:57] offset:10880
	ds_write_b64 v144, v[46:47] offset:13056
	ds_write_b64 v144, v[54:55] offset:15232
	ds_write_b64 v144, v[52:53] offset:17408
	ds_write_b64 v144, v[60:61] offset:19584
	ds_write_b64 v144, v[58:59] offset:21760
	ds_write_b64 v144, v[64:65] offset:23936
	ds_write_b64 v144, v[62:63] offset:26112
	ds_write_b64 v144, v[68:69] offset:28288
	ds_write_b64 v144, v[66:67] offset:30464
	ds_write_b64 v144, v[70:71] offset:32640
	s_waitcnt lgkmcnt(0)
	s_barrier
	s_nop 0
	v_and_b32_e32 v29, 63, v28
	v_cmp_eq_u32_e32 vcc, 0, v29
	s_and_saveexec_b64 s[0:1], vcc
	v_add_f32_e32 v26, v26, v27
	v_ashrrev_i32_e32 v27, 4, v28
	v_add_u32_e32 v27, 0, v27
	v_add_u32_e32 v27, 0x11000, v27
	ds_write_b32 v27, v26
	s_or_b64 exec, exec, s[0:1]
	v_mov_b32_e32 v26, s86
	v_mov_b32_e32 v45, v37
	v_mov_b32_e32 v44, v36
	s_waitcnt lgkmcnt(0)
	s_barrier
	ds_read_b128 v[30:33], v26
	ds_read_b128 v[26:29], v26 offset:16
	ds_read_b64 v[46:47], v144
	ds_read_b64 v[48:49], v149
	s_and_saveexec_b64 s[0:1], s[4:5]
	s_xor_b64 s[0:1], exec, s[0:1]
	s_cbranch_execz .LBB0_1345
	v_pk_mul_f32 v[50:51], v[44:45], s[16:17] op_sel:[0,0] op_sel_hi:[0,1]
	s_waitcnt lgkmcnt(0)
	v_sub_f32_e32 v34, v48, v46
	v_pk_fma_f32 v[42:43], v[44:45], s[16:17], v[50:51] op_sel:[1,1,0] op_sel_hi:[1,0,1] neg_lo:[0,1,0]
	s_nop 0
	v_pk_mul_f32 v[42:43], v[34:35], v[42:43] op_sel_hi:[0,1]

.LBB0_1422:
	v_add_u32_e32 v38, 0, v34
	v_add_u32_e32 v40, 0, v94
	ds_read_b64 v[38:39], v38
	ds_read_b64 v[40:41], v40
	v_add_u32_e32 v94, 0x880, v94
	v_add_u32_e32 v34, 0x880, v34
	v_add_u32_e32 v191, 0, v141
	ds_read_b64 v[192:193], v191
	v_add_u32_e32 v194, s6, v140
	v_cmp_lt_i32_e32 vcc, 0, v194
	s_addk_i32 s6, 0x100
	v_add_u32_e32 v141, 0x800, v141
	v_subbrev_co_u32_e64 v195, s[0:1], 0, v194, vcc
	v_lshl_add_u32 v195, v195, 1, 0
	v_add_u32_e32 v196, 0, v139
	v_add_u32_e32 v197, 0x19400, v195
	v_add_u32_e32 v198, 0x19400, v196
	v_add_u32_e32 v199, 0x1b400, v195
	v_add_u32_e32 v200, 0x1b400, v196
	ds_read_b32 v46, v198
	ds_read_u16 v199, v199
	ds_read_u16 v197, v197
	ds_read_b32 v200, v200
	v_cmp_gt_i32_e64 s[0:1], s3, v194
	s_waitcnt lgkmcnt(5)
	v_pk_add_f32 v[38:39], v[38:39], v[40:41]
	s_waitcnt lgkmcnt(4)
	v_pk_fma_f32 v[38:39], v[26:27], v[192:193], v[38:39]
	v_mov_b32_e32 v40, v194
	s_waitcnt lgkmcnt(3)
	v_lshlrev_b32_e32 v44, 16, v46
	s_waitcnt lgkmcnt(2)
	v_lshlrev_b32_e32 v41, 16, v199
	v_cndmask_b32_e32 v43, 0, v41, vcc
	s_waitcnt lgkmcnt(1)
	v_lshlrev_b32_e32 v42, 16, v197
	v_cndmask_b32_e32 v42, 0, v42, vcc
	v_add_u32_e32 v139, 0x200, v139
	s_cmpk_eq_i32 s6, 0x800
	s_waitcnt lgkmcnt(0)
	v_lshlrev_b32_e32 v45, 16, v200
	v_pk_mul_f32 v[44:45], v[32:33], v[44:45]
	v_and_b32_e32 v41, 0xffff0000, v200
	v_pk_fma_f32 v[42:43], v[30:31], v[42:43], v[44:45]
	v_and_b32_e32 v44, 0xffff0000, v46
	v_cndmask_b32_e64 v45, 0, v41, s[0:1]
	v_cndmask_b32_e64 v44, 0, v44, s[0:1]
	v_pk_fma_f32 v[42:43], v[36:37], v[44:45], v[42:43]
	v_ashrrev_i32_e32 v41, 31, v40
	v_pk_add_f32 v[42:43], v[28:29], v[42:43]
	v_lshl_add_u64 v[40:41], v[40:41], 2, s[4:5]
	v_pk_mul_f32 v[38:39], v[38:39], v[42:43]
	global_store_dword v[40:41], v38, off
	v_add_co_u32_e32 v40, vcc, 0x4000, v40
	s_nop 1
	v_addc_co_u32_e32 v41, vcc, 0, v41, vcc
	global_store_dword v[40:41], v39, off
	s_cbranch_scc0 .LBB0_1422
	s_andn2_b64 vcc, exec, s[80:81]
	s_mov_b32 s74, s82
	s_barrier
	s_cbranch_vccnz .LBB0_1195
	v_readlane_b32 s64, v238, 16
	s_movk_i32 s3, 0xff
	v_mov_b32_e32 v11, 0
	s_mov_b64 s[6:7], 0x4000
	v_mov_b32_e32 v1, 0x3000
	v_mov_b32_e32 v22, 0x6000
	v_mov_b32_e32 v23, 0x1000
	v_mov_b32_e32 v24, 0x4000
	v_mov_b32_e32 v25, 0x7000
	v_mov_b32_e32 v26, 0x2000
	v_mov_b32_e32 v27, 0x5000
	v_mov_b32_e32 v28, 0x8000
	s_movk_i32 s25, 0x100
	s_movk_i32 s26, 0x2000
	s_movk_i32 s27, 0x7200
	s_add_i32 s33, 0, 0x800
	s_movk_i32 s50, 0x7fff
	v_mov_b32_e32 v29, 0x1ff
	s_mov_b32 s14, s2
	v_readlane_b32 s65, v238, 17

.LBB0_3409:
	v_add_u32_e32 v49, 0, v43
	ds_read_b64 v[74:75], v49
	v_add_u32_e32 v49, 0, v45
	ds_read_b64 v[76:77], v49
	v_add_u32_e32 v49, s15, v128
	v_cmp_lt_i32_e32 vcc, 0, v49
	v_add_u32_e32 v57, 0, v47
	v_add_u32_e32 v51, 0, v27
	v_subbrev_co_u32_e64 v53, s[0:1], 0, v49, vcc
	v_lshl_add_u32 v53, v53, 1, 0
	v_add_u32_e32 v55, 0x15400, v53
	v_add_u32_e32 v59, 0x15400, v57
	v_cmp_gt_i32_e64 s[0:1], s87, v49
	v_add_u32_e32 v49, 0x17400, v53
	v_add_u32_e32 v53, 0x17400, v57
	ds_read_b64 v[188:189], v51
	ds_read_b32 v57, v59
	ds_read_u16 v49, v49
	ds_read_u16 v55, v55
	ds_read_b32 v190, v53
	s_addk_i32 s15, 0x100
	v_add_u32_e32 v47, 0x200, v47
	s_waitcnt lgkmcnt(5)
	v_pk_add_f32 v[74:75], v[74:75], v[76:77]
	s_waitcnt lgkmcnt(4)
	v_pk_fma_f32 v[74:75], v[72:73], v[188:189], v[74:75]
	s_waitcnt lgkmcnt(2)
	v_lshlrev_b32_e32 v49, 16, v49
	v_cndmask_b32_e32 v77, 0, v49, vcc
	s_waitcnt lgkmcnt(1)
	v_lshlrev_b32_e32 v55, 16, v55
	v_lshlrev_b32_e32 v78, 16, v57
	v_cndmask_b32_e32 v76, 0, v55, vcc
	v_and_b32_e32 v53, 0xffff0000, v57
	s_waitcnt lgkmcnt(0)
	v_lshlrev_b32_e32 v79, 16, v190
	v_pk_mul_f32 v[78:79], v[32:33], v[78:79]
	v_and_b32_e32 v49, 0xffff0000, v190
	v_pk_fma_f32 v[76:77], v[28:29], v[76:77], v[78:79]
	v_cndmask_b32_e64 v79, 0, v49, s[0:1]
	v_cndmask_b32_e64 v78, 0, v53, s[0:1]
	v_pk_fma_f32 v[76:77], v[70:71], v[78:79], v[76:77]
	v_add_u32_e32 v27, 0x800, v27
	v_pk_add_f32 v[76:77], v[30:31], v[76:77]
	v_add_u32_e32 v45, 0x880, v45
	v_pk_mul_f32 v[74:75], v[74:75], v[76:77]
	v_add_u32_e32 v43, 0x880, v43
	s_cmpk_eq_i32 s15, 0x800
	ds_write_b64 v51, v[74:75]
	s_cbranch_scc0 .LBB0_3409
	s_andn2_b64 vcc, exec, s[78:79]
	s_mov_b64 s[0:1], -1
	s_waitcnt lgkmcnt(0)
	s_barrier
	s_cbranch_vccnz .LBB0_3412
	v_mov_b32_e32 v28, v133
	s_mov_b64 s[0:1], 0
	v_ashrrev_i32_e32 v29, 31, v28
	v_lshl_add_u64 v[88:89], v[28:29], 3, s[76:77]
	v_add_co_u32_e32 v28, vcc, 0x10000, v88
	s_nop 1
	v_addc_co_u32_e32 v29, vcc, 0, v89, vcc
	v_add_co_u32_e32 v30, vcc, 0x11000, v88
	s_nop 1
	v_addc_co_u32_e32 v31, vcc, 0, v89, vcc
	v_add_co_u32_e32 v32, vcc, 0x12000, v88
	s_nop 1
	v_addc_co_u32_e32 v33, vcc, 0, v89, vcc
	v_add_co_u32_e32 v72, vcc, 0x13000, v88
	s_nop 1
	v_addc_co_u32_e32 v73, vcc, 0, v89, vcc
	global_load_dwordx2 v[70:71], v[28:29], off
	s_nop 0
	global_load_dwordx2 v[30:31], v[30:31], off
	s_nop 0
	global_load_dwordx2 v[28:29], v[32:33], off
	s_nop 0
	global_load_dwordx2 v[32:33], v[72:73], off
	v_add_co_u32_e32 v72, vcc, 0x14000, v88
	s_nop 1
	v_addc_co_u32_e32 v73, vcc, 0, v89, vcc
	v_add_co_u32_e32 v74, vcc, 0x15000, v88
	s_nop 1
	v_addc_co_u32_e32 v75, vcc, 0, v89, vcc
	v_add_co_u32_e32 v76, vcc, 0x16000, v88
	s_nop 1
	v_addc_co_u32_e32 v77, vcc, 0, v89, vcc
	v_add_co_u32_e32 v80, vcc, 0x17000, v88
	s_nop 1
	v_addc_co_u32_e32 v81, vcc, 0, v89, vcc
	global_load_dwordx2 v[78:79], v[72:73], off
	s_nop 0
	global_load_dwordx2 v[74:75], v[74:75], off
	s_nop 0
	global_load_dwordx2 v[72:73], v[76:77], off
	s_nop 0
	global_load_dwordx2 v[76:77], v[80:81], off
	v_add_co_u32_e32 v80, vcc, 0x18000, v88
	s_nop 1
	v_addc_co_u32_e32 v81, vcc, 0, v89, vcc
	v_add_co_u32_e32 v82, vcc, 0x19000, v88
	s_nop 1
	v_addc_co_u32_e32 v83, vcc, 0, v89, vcc
	v_add_co_u32_e32 v84, vcc, 0x1a000, v88
	s_nop 1
	v_addc_co_u32_e32 v85, vcc, 0, v89, vcc
	v_add_co_u32_e32 v90, vcc, 0x1b000, v88
	s_nop 1
	v_addc_co_u32_e32 v91, vcc, 0, v89, vcc
	global_load_dwordx2 v[86:87], v[80:81], off
	s_nop 0
	global_load_dwordx2 v[82:83], v[82:83], off
	s_nop 0
	global_load_dwordx2 v[80:81], v[84:85], off
	s_nop 0
	global_load_dwordx2 v[84:85], v[90:91], off
	v_add_co_u32_e32 v90, vcc, 0x1c000, v88
	s_nop 1
	v_addc_co_u32_e32 v91, vcc, 0, v89, vcc
	v_add_co_u32_e32 v92, vcc, 0x1d000, v88
	s_nop 1
	v_addc_co_u32_e32 v93, vcc, 0, v89, vcc
	v_add_co_u32_e32 v98, vcc, 0x1e000, v88
	s_nop 1
	v_addc_co_u32_e32 v99, vcc, 0, v89, vcc
	v_add_co_u32_e32 v100, vcc, 0x1f000, v88
	s_nop 1
	v_addc_co_u32_e32 v101, vcc, 0, v89, vcc
	global_load_dwordx2 v[94:95], v[90:91], off
	s_nop 0
	global_load_dwordx2 v[90:91], v[92:93], off
	global_load_dwordx2 v[88:89], v[98:99], off
	s_nop 0
	global_load_dwordx2 v[92:93], v[100:101], off

.LBB0_3495:
	v_add_u32_e32 v38, 0, v34
	v_add_u32_e32 v40, 0, v96
	ds_read_b64 v[38:39], v38
	ds_read_b64 v[40:41], v40
	v_add_u32_e32 v96, 0x880, v96
	v_add_u32_e32 v34, 0x880, v34
	v_add_u32_e32 v191, 0, v129
	ds_read_b64 v[192:193], v191
	v_add_u32_e32 v194, s6, v128
	v_cmp_lt_i32_e32 vcc, 0, v194
	s_addk_i32 s6, 0x100
	v_add_u32_e32 v129, 0x800, v129
	v_subbrev_co_u32_e64 v195, s[0:1], 0, v194, vcc
	v_lshl_add_u32 v195, v195, 1, 0
	v_add_u32_e32 v196, 0, v127
	v_add_u32_e32 v197, 0x19400, v195
	v_add_u32_e32 v198, 0x19400, v196
	v_add_u32_e32 v199, 0x1b400, v195
	v_add_u32_e32 v200, 0x1b400, v196
	ds_read_b32 v46, v198
	ds_read_u16 v199, v199
	ds_read_u16 v197, v197
	ds_read_b32 v200, v200
	v_cmp_gt_i32_e64 s[0:1], s87, v194
	s_waitcnt lgkmcnt(5)
	v_pk_add_f32 v[38:39], v[38:39], v[40:41]
	s_waitcnt lgkmcnt(4)
	v_pk_fma_f32 v[38:39], v[26:27], v[192:193], v[38:39]
	v_mov_b32_e32 v40, v194
	s_waitcnt lgkmcnt(3)
	v_lshlrev_b32_e32 v44, 16, v46
	s_waitcnt lgkmcnt(2)
	v_lshlrev_b32_e32 v41, 16, v199
	v_cndmask_b32_e32 v43, 0, v41, vcc
	s_waitcnt lgkmcnt(1)
	v_lshlrev_b32_e32 v42, 16, v197
	v_cndmask_b32_e32 v42, 0, v42, vcc
	v_add_u32_e32 v127, 0x200, v127
	s_cmpk_eq_i32 s6, 0x800
	s_waitcnt lgkmcnt(0)
	v_lshlrev_b32_e32 v45, 16, v200
	v_pk_mul_f32 v[44:45], v[32:33], v[44:45]
	v_and_b32_e32 v41, 0xffff0000, v200
	v_pk_fma_f32 v[42:43], v[30:31], v[42:43], v[44:45]
	v_and_b32_e32 v44, 0xffff0000, v46
	v_cndmask_b32_e64 v45, 0, v41, s[0:1]
	v_cndmask_b32_e64 v44, 0, v44, s[0:1]
	v_pk_fma_f32 v[42:43], v[36:37], v[44:45], v[42:43]
	v_ashrrev_i32_e32 v41, 31, v40
	v_pk_add_f32 v[42:43], v[28:29], v[42:43]
	v_lshl_add_u64 v[40:41], v[40:41], 2, s[4:5]
	v_pk_mul_f32 v[38:39], v[38:39], v[42:43]
	global_store_dword v[40:41], v38, off
	v_add_co_u32_e32 v40, vcc, 0x4000, v40
	s_nop 1
	v_addc_co_u32_e32 v41, vcc, 0, v41, vcc
	global_store_dword v[40:41], v39, off
	s_cbranch_scc0 .LBB0_3495
	s_and_b64 vcc, exec, s[76:77]
	s_mov_b32 s70, s78
	s_barrier
	s_cbranch_vccz .LBB0_3258
